# mixers layer 0: latent-C units rebalanced 5/11 between workgroups 0-127 (which also run the context attention-A unit) and 128-255
# speedup vs baseline: 1.0072x; 1.0002x over previous
.LBB0_228:
	s_cmpk_gt_i32 s12, 0x7ff
	s_waitcnt vmcnt(0)
	s_barrier
	s_cbranch_scc1 .LBB0_383
	v_readlane_b32 s0, v252, 19
	s_lshl_b32 s0, s0, 3
	v_readlane_b32 s1, v252, 20
	v_writelane_b32 v252, s0, 28
	s_nop 0
	v_readlane_b32 s35, v252, 26
	s_movk_i32 s100, 0x7ff
	s_mov_b32 s101, 0
	v_readlane_b32 s0, v253, 6
	s_cmp_lt_u32 s0, 12
	s_cbranch_scc0 .Lc2b_go_a
	s_cmpk_eq_i32 s94, 0x100
	s_cbranch_scc0 .Lc2b_go_a
	s_cmpk_lt_i32 s35, 0x80
	s_cbranch_scc0 .Lc2b_hi_a
	s_movk_i32 s100, 0x4ff
	s_branch .Lc2b_go_a
.Lc2b_hi_a:
	s_add_i32 s101, s35, 0x480

.LBB0_230:
	s_or_b64 exec, exec, s[0:1]
	s_mov_b32 s0, 0xff800000
	v_max3_f32 v64, v109, s0, v108
	v_max3_f32 v64, v64, v111, v110
	v_max3_f32 v64, v64, v133, v132
	v_max3_f32 v64, v64, v135, v134
	v_max3_f32 v64, v64, v137, v136
	v_max3_f32 v64, v64, v121, v120
	v_max3_f32 v64, v64, v123, v122
	v_max3_f32 v64, v64, v129, v128
	v_max3_f32 v64, v64, v131, v130
	v_max3_f32 v64, v64, v101, v100
	v_max3_f32 v64, v64, v103, v102
	v_max3_f32 v64, v64, v113, v112
	v_max3_f32 v64, v64, v115, v114
	v_max3_f32 v64, v64, v117, v116
	v_max3_f32 v64, v64, v119, v118
	v_max3_f32 v64, v64, v125, v124
	v_max3_f32 v64, v64, v127, v126
	v_max3_f32 v64, v64, v97, v96
	v_max3_f32 v64, v64, v99, v98
	v_max3_f32 v64, v64, v105, v104
	v_max3_f32 v64, v64, v107, v106
	v_max3_f32 v64, v64, v81, v80
	v_max3_f32 v64, v64, v83, v82
	v_max3_f32 v64, v64, v93, v92
	v_max3_f32 v64, v64, v95, v94
	v_max3_f32 v64, v64, v85, v84
	v_max3_f32 v64, v64, v87, v86
	v_max3_f32 v64, v64, v89, v88
	v_max3_f32 v64, v64, v91, v90
	v_max3_f32 v64, v64, v73, v72
	v_max3_f32 v64, v64, v139, v75
	v_max3_f32 v64, v64, v167, v166
	v_max3_f32 v64, v64, v169, v168
	v_max3_f32 v64, v64, v160, v159
	v_max3_f32 v64, v64, v162, v161
	v_max3_f32 v64, v64, v164, v163
	v_max3_f32 v64, v64, v48, v49
	v_max3_f32 v64, v64, v50, v51
	v_max3_f32 v64, v64, v32, v33
	v_max3_f32 v64, v64, v34, v35
	v_max3_f32 v64, v64, v36, v37
	v_max3_f32 v64, v64, v38, v39
	v_max3_f32 v64, v64, v24, v25
	v_max3_f32 v64, v64, v26, v27
	v_max3_f32 v64, v64, v56, v57
	v_max3_f32 v64, v64, v58, v59
	v_max3_f32 v64, v64, v40, v41
	v_max3_f32 v64, v64, v42, v43
	v_max3_f32 v64, v64, v44, v45
	v_max3_f32 v64, v64, v46, v47
	v_max3_f32 v64, v64, v28, v29
	v_max3_f32 v64, v64, v30, v31
	v_max3_f32 v64, v64, v60, v61
	v_max3_f32 v64, v64, v62, v63
	v_max3_f32 v64, v64, v52, v53
	v_max3_f32 v64, v64, v54, v55
	v_max3_f32 v64, v64, v20, v21
	v_max3_f32 v64, v64, v22, v23
	v_max3_f32 v64, v64, v16, v17
	v_max3_f32 v64, v64, v18, v19
	v_max3_f32 v64, v64, v12, v13
	v_max3_f32 v64, v64, v14, v15
	v_max3_f32 v64, v64, v8, v9
	v_max3_f32 v64, v64, v10, v11
	v_and_b32_e32 v66, 64, v199
	v_max3_f32 v64, v64, v4, v5
	v_xor_b32_e32 v65, 16, v199
	v_add_u32_e32 v66, 64, v66
	v_max3_f32 v64, v64, v6, v7
	v_cmp_lt_i32_e32 vcc, v65, v66
	v_max3_f32 v64, v64, v0, v1
	v_max3_f32 v64, v64, v2, v3
	v_cndmask_b32_e32 v65, v199, v65, vcc
	v_lshlrev_b32_e32 v65, 2, v65
	ds_bpermute_b32 v67, v65, v64
	v_lshlrev_b32_e32 v176, 1, v156
	s_mov_b64 s[0:1], 0x1000
	s_mov_b32 m0, s10
	s_waitcnt vmcnt(8)
	s_waitcnt lgkmcnt(0)
	v_max_f32_e32 v67, v67, v67
	v_max_f32_e32 v67, v64, v67
	v_xor_b32_e32 v64, 32, v199
	v_cmp_lt_i32_e32 vcc, v64, v66
	s_barrier
	s_lshl_b32 s70, s95, 1
	v_cndmask_b32_e32 v64, v199, v64, vcc
	v_lshlrev_b32_e32 v64, 2, v64
	ds_bpermute_b32 v66, v64, v67
	s_add_i32 s35, s35, s94
	s_cmp_gt_i32 s35, s100
	s_cbranch_scc0 .Lc2b_c_a
	s_cmp_eq_u32 s101, 0
	s_cbranch_scc1 .Lc2b_c_a
	s_mov_b32 s35, s101
	s_mov_b32 s101, 0
	s_movk_i32 s100, 0x7ff
	s_cmp_gt_i32 s35, s100
.Lc2b_c_a:
	s_waitcnt lgkmcnt(0)
	v_max_f32_e32 v66, v66, v66
	v_max_f32_e32 v66, v67, v66
	v_sub_f32_e32 v67, v109, v66
	v_exp_f32_e32 v67, v67
	v_sub_f32_e32 v68, v108, v66
	v_exp_f32_e32 v68, v68
	v_sub_f32_e32 v69, v111, v66
	v_exp_f32_e32 v69, v69
	v_sub_f32_e32 v71, v110, v66
	v_exp_f32_e32 v71, v71
	v_sub_f32_e32 v74, v133, v66
	v_add_f32_e32 v70, 0, v67
	v_exp_f32_e32 v74, v74
	v_add_f32_e32 v70, v68, v70
	v_add_f32_e32 v70, v69, v70
	v_add_f32_e32 v70, v71, v70
	v_add_f32_e32 v76, v74, v70
	v_sub_f32_e32 v70, v132, v66
	v_exp_f32_e32 v108, v70
	v_sub_f32_e32 v70, v135, v66
	v_exp_f32_e32 v110, v70
	v_sub_f32_e32 v70, v134, v66
	v_exp_f32_e32 v132, v70
	v_sub_f32_e32 v70, v137, v66
	v_exp_f32_e32 v70, v70
	v_sub_f32_e32 v77, v136, v66
	v_add_f32_e32 v76, v108, v76
	v_exp_f32_e32 v77, v77
	v_sub_f32_e32 v78, v121, v66
	v_add_f32_e32 v76, v110, v76
	v_exp_f32_e32 v78, v78
	v_sub_f32_e32 v79, v120, v66
	v_add_f32_e32 v76, v132, v76
	v_exp_f32_e32 v109, v79
	v_sub_f32_e32 v79, v123, v66
	v_add_f32_e32 v76, v70, v76
	v_exp_f32_e32 v111, v79
	v_sub_f32_e32 v79, v122, v66
	v_add_f32_e32 v76, v77, v76
	v_exp_f32_e32 v122, v79
	v_sub_f32_e32 v79, v129, v66
	v_add_f32_e32 v76, v78, v76
	v_exp_f32_e32 v129, v79
	v_sub_f32_e32 v79, v128, v66
	v_add_f32_e32 v76, v109, v76
	v_exp_f32_e32 v133, v79
	v_sub_f32_e32 v79, v131, v66
	v_add_f32_e32 v76, v111, v76
	v_exp_f32_e32 v79, v79
	v_sub_f32_e32 v120, v130, v66
	v_add_f32_e32 v76, v122, v76
	v_exp_f32_e32 v120, v120
	v_sub_f32_e32 v101, v101, v66
	v_add_f32_e32 v76, v129, v76
	v_exp_f32_e32 v121, v101
	v_sub_f32_e32 v100, v100, v66
	v_add_f32_e32 v76, v133, v76
	v_exp_f32_e32 v123, v100
	v_sub_f32_e32 v100, v103, v66
	v_add_f32_e32 v76, v79, v76
	v_exp_f32_e32 v128, v100
	v_add_f32_e32 v76, v120, v76
	v_add_f32_e32 v76, v121, v76
	v_add_f32_e32 v76, v123, v76
	v_add_f32_e32 v100, v128, v76
	v_sub_f32_e32 v76, v102, v66
	v_exp_f32_e32 v130, v76
	v_sub_f32_e32 v76, v113, v66
	v_exp_f32_e32 v131, v76
	v_sub_f32_e32 v76, v112, v66
	v_exp_f32_e32 v134, v76
	v_sub_f32_e32 v76, v115, v66
	v_exp_f32_e32 v76, v76
	v_add_f32_e32 v100, v130, v100
	v_add_f32_e32 v100, v131, v100
	v_add_f32_e32 v100, v134, v100
	v_add_f32_e32 v102, v76, v100
	v_sub_f32_e32 v100, v114, v66
	v_exp_f32_e32 v100, v100
	v_sub_f32_e32 v101, v117, v66
	v_exp_f32_e32 v101, v101
	v_sub_f32_e32 v103, v116, v66
	v_exp_f32_e32 v103, v103
	v_sub_f32_e32 v112, v119, v66
	v_exp_f32_e32 v112, v112
	v_add_f32_e32 v102, v100, v102
	v_add_f32_e32 v102, v101, v102
	v_add_f32_e32 v102, v103, v102
	v_add_f32_e32 v113, v112, v102
	v_sub_f32_e32 v102, v118, v66
	v_exp_f32_e32 v114, v102
	v_sub_f32_e32 v102, v125, v66
	v_exp_f32_e32 v116, v102
	v_sub_f32_e32 v102, v124, v66
	v_exp_f32_e32 v117, v102
	v_sub_f32_e32 v102, v127, v66
	v_exp_f32_e32 v102, v102
	v_add_f32_e32 v113, v114, v113
	v_add_f32_e32 v113, v116, v113
	v_add_f32_e32 v113, v117, v113
	v_add_f32_e32 v118, v102, v113
	v_sub_f32_e32 v113, v126, v66
	v_exp_f32_e32 v113, v113
	v_sub_f32_e32 v97, v97, v66
	v_exp_f32_e32 v97, v97
	v_sub_f32_e32 v96, v96, v66
	v_exp_f32_e32 v115, v96
	v_sub_f32_e32 v96, v99, v66
	v_exp_f32_e32 v99, v96
	v_add_f32_e32 v96, v113, v118
	v_add_f32_e32 v96, v97, v96
	v_add_f32_e32 v96, v115, v96
	v_add_f32_e32 v124, v99, v96
	v_sub_f32_e32 v96, v98, v66
	v_exp_f32_e32 v118, v96
	v_sub_f32_e32 v96, v105, v66
	v_exp_f32_e32 v119, v96
	v_sub_f32_e32 v96, v104, v66
	v_exp_f32_e32 v125, v96
	v_sub_f32_e32 v96, v107, v66
	v_exp_f32_e32 v96, v96
	v_add_f32_e32 v98, v118, v124
	v_add_f32_e32 v98, v119, v98
	v_add_f32_e32 v98, v125, v98
	v_add_f32_e32 v107, v96, v98
	v_sub_f32_e32 v98, v106, v66
	v_exp_f32_e32 v98, v98
	v_sub_f32_e32 v81, v81, v66
	v_exp_f32_e32 v104, v81
	v_sub_f32_e32 v80, v80, v66
	v_exp_f32_e32 v105, v80
	v_sub_f32_e32 v80, v83, v66
	v_exp_f32_e32 v106, v80
	v_add_f32_e32 v80, v98, v107
	v_add_f32_e32 v80, v104, v80
	v_add_f32_e32 v80, v105, v80
	v_add_f32_e32 v81, v106, v80
	v_sub_f32_e32 v80, v82, v66
	v_exp_f32_e32 v107, v80
	v_sub_f32_e32 v80, v93, v66
	v_exp_f32_e32 v124, v80
	v_sub_f32_e32 v80, v92, v66
	v_exp_f32_e32 v126, v80
	v_sub_f32_e32 v80, v95, v66
	v_exp_f32_e32 v80, v80
	v_add_f32_e32 v81, v107, v81
	v_add_f32_e32 v81, v124, v81
	v_add_f32_e32 v81, v126, v81
	v_add_f32_e32 v83, v80, v81
	v_sub_f32_e32 v81, v94, v66
	v_exp_f32_e32 v81, v81
	v_sub_f32_e32 v82, v85, v66
	v_exp_f32_e32 v82, v82
	v_sub_f32_e32 v84, v84, v66
	v_exp_f32_e32 v84, v84
	v_sub_f32_e32 v85, v87, v66
	v_exp_f32_e32 v85, v85
	v_add_f32_e32 v83, v81, v83
	v_add_f32_e32 v83, v82, v83
	v_add_f32_e32 v83, v84, v83
	v_add_f32_e32 v92, v85, v83
	v_sub_f32_e32 v83, v86, v66
	v_exp_f32_e32 v87, v83
	v_sub_f32_e32 v83, v89, v66
	v_exp_f32_e32 v89, v83
	v_sub_f32_e32 v83, v88, v66
	v_exp_f32_e32 v94, v83
	v_sub_f32_e32 v83, v91, v66
	v_exp_f32_e32 v83, v83
	v_add_f32_e32 v86, v87, v92
	v_add_f32_e32 v86, v89, v86
	v_add_f32_e32 v86, v94, v86
	v_add_f32_e32 v91, v83, v86
	v_sub_f32_e32 v86, v90, v66
	v_exp_f32_e32 v86, v86
	v_sub_f32_e32 v73, v73, v66
	v_exp_f32_e32 v73, v73
	v_sub_f32_e32 v72, v72, v66
	v_exp_f32_e32 v88, v72
	v_sub_f32_e32 v72, v139, v66
	v_exp_f32_e32 v95, v72
	v_add_f32_e32 v72, v86, v91
	v_add_f32_e32 v72, v73, v72
	v_add_f32_e32 v72, v88, v72
	v_add_f32_e32 v90, v95, v72
	v_sub_f32_e32 v72, v75, v66
	v_exp_f32_e32 v75, v72
	v_sub_f32_e32 v72, v167, v66
	v_exp_f32_e32 v127, v72
	v_sub_f32_e32 v72, v166, v66
	v_exp_f32_e32 v135, v72
	v_sub_f32_e32 v72, v169, v66
	v_exp_f32_e32 v72, v72
	v_sub_f32_e32 v91, v168, v66
	v_add_f32_e32 v90, v75, v90
	v_exp_f32_e32 v136, v91
	v_sub_f32_e32 v91, v160, v66
	v_add_f32_e32 v90, v127, v90
	v_exp_f32_e32 v137, v91
	v_sub_f32_e32 v91, v159, v66
	v_add_f32_e32 v90, v135, v90
	v_exp_f32_e32 v138, v91
	v_sub_f32_e32 v91, v162, v66
	v_add_f32_e32 v90, v72, v90
	v_exp_f32_e32 v139, v91
	v_sub_f32_e32 v91, v161, v66
	v_add_f32_e32 v90, v136, v90
	v_exp_f32_e32 v159, v91
	v_sub_f32_e32 v91, v164, v66
	v_add_f32_e32 v90, v137, v90
	v_exp_f32_e32 v160, v91
	v_sub_f32_e32 v91, v163, v66
	v_add_f32_e32 v90, v138, v90
	v_exp_f32_e32 v161, v91
	v_sub_f32_e32 v48, v48, v66
	v_add_f32_e32 v90, v139, v90
	v_exp_f32_e32 v48, v48
	v_sub_f32_e32 v49, v49, v66
	v_add_f32_e32 v90, v159, v90
	v_exp_f32_e32 v49, v49
	v_sub_f32_e32 v50, v50, v66
	v_add_f32_e32 v90, v160, v90
	v_exp_f32_e32 v50, v50
	v_sub_f32_e32 v51, v51, v66
	v_add_f32_e32 v90, v161, v90
	v_exp_f32_e32 v51, v51
	v_sub_f32_e32 v32, v32, v66
	v_add_f32_e32 v90, v48, v90
	v_exp_f32_e32 v162, v32
	v_add_f32_e32 v32, v49, v90
	v_add_f32_e32 v32, v50, v32
	v_add_f32_e32 v32, v51, v32
	v_add_f32_e32 v90, v162, v32
	v_sub_f32_e32 v32, v33, v66
	v_exp_f32_e32 v33, v32
	v_sub_f32_e32 v32, v34, v66
	v_exp_f32_e32 v163, v32
	v_sub_f32_e32 v32, v35, v66
	v_exp_f32_e32 v164, v32
	v_sub_f32_e32 v32, v36, v66
	v_exp_f32_e32 v32, v32
	v_sub_f32_e32 v35, v37, v66
	v_add_f32_e32 v34, v33, v90
	v_exp_f32_e32 v165, v35
	v_sub_f32_e32 v35, v38, v66
	v_add_f32_e32 v34, v163, v34
	v_exp_f32_e32 v166, v35
	v_sub_f32_e32 v35, v39, v66
	v_add_f32_e32 v34, v164, v34
	v_exp_f32_e32 v167, v35
	v_sub_f32_e32 v24, v24, v66
	v_add_f32_e32 v34, v32, v34
	v_exp_f32_e32 v168, v24
	v_add_f32_e32 v24, v165, v34
	v_add_f32_e32 v24, v166, v24
	v_add_f32_e32 v24, v167, v24
	v_add_f32_e32 v34, v168, v24
	v_sub_f32_e32 v24, v25, v66
	v_exp_f32_e32 v25, v24
	v_sub_f32_e32 v24, v26, v66
	v_exp_f32_e32 v169, v24
	v_sub_f32_e32 v24, v27, v66
	v_exp_f32_e32 v170, v24
	v_sub_f32_e32 v24, v56, v66
	v_exp_f32_e32 v24, v24
	v_sub_f32_e32 v27, v57, v66
	v_add_f32_e32 v26, v25, v34
	v_exp_f32_e32 v171, v27
	v_sub_f32_e32 v27, v58, v66
	v_add_f32_e32 v26, v169, v26
	v_exp_f32_e32 v172, v27
	v_sub_f32_e32 v27, v59, v66
	v_add_f32_e32 v26, v170, v26
	v_exp_f32_e32 v173, v27
	v_sub_f32_e32 v27, v40, v66
	v_add_f32_e32 v26, v24, v26
	v_exp_f32_e32 v174, v27
	v_sub_f32_e32 v27, v41, v66
	v_add_f32_e32 v26, v171, v26
	v_exp_f32_e32 v175, v27
	v_sub_f32_e32 v27, v42, v66
	v_add_f32_e32 v26, v172, v26
	v_exp_f32_e32 v178, v27
	v_sub_f32_e32 v27, v43, v66
	v_add_f32_e32 v26, v173, v26
	v_exp_f32_e32 v179, v27
	v_sub_f32_e32 v27, v44, v66
	v_add_f32_e32 v26, v174, v26
	v_exp_f32_e32 v180, v27
	v_sub_f32_e32 v27, v45, v66
	v_add_f32_e32 v26, v175, v26
	v_exp_f32_e32 v181, v27
	v_sub_f32_e32 v27, v46, v66
	v_add_f32_e32 v26, v178, v26
	v_exp_f32_e32 v182, v27
	v_sub_f32_e32 v27, v47, v66
	v_add_f32_e32 v26, v179, v26
	v_exp_f32_e32 v183, v27
	v_sub_f32_e32 v27, v28, v66
	v_add_f32_e32 v26, v180, v26
	v_exp_f32_e32 v184, v27
	v_sub_f32_e32 v27, v29, v66
	v_add_f32_e32 v26, v181, v26
	v_exp_f32_e32 v185, v27
	v_sub_f32_e32 v27, v30, v66
	v_add_f32_e32 v26, v182, v26
	v_exp_f32_e32 v186, v27
	v_sub_f32_e32 v27, v31, v66
	v_add_f32_e32 v26, v183, v26
	v_exp_f32_e32 v187, v27
	v_sub_f32_e32 v27, v60, v66
	v_add_f32_e32 v26, v184, v26
	v_exp_f32_e32 v188, v27
	v_sub_f32_e32 v27, v61, v66
	v_add_f32_e32 v26, v185, v26
	v_exp_f32_e32 v189, v27
	v_sub_f32_e32 v27, v62, v66
	v_add_f32_e32 v26, v186, v26
	v_exp_f32_e32 v207, v27
	v_sub_f32_e32 v27, v63, v66
	v_add_f32_e32 v26, v187, v26
	v_exp_f32_e32 v208, v27
	v_sub_f32_e32 v27, v52, v66
	v_add_f32_e32 v26, v188, v26
	v_exp_f32_e32 v209, v27
	v_sub_f32_e32 v27, v53, v66
	v_add_f32_e32 v26, v189, v26
	v_exp_f32_e32 v210, v27
	v_sub_f32_e32 v27, v54, v66
	v_add_f32_e32 v26, v207, v26
	v_exp_f32_e32 v211, v27
	v_sub_f32_e32 v27, v55, v66
	v_add_f32_e32 v26, v208, v26
	v_exp_f32_e32 v212, v27
	v_sub_f32_e32 v20, v20, v66
	v_add_f32_e32 v26, v209, v26
	v_exp_f32_e32 v213, v20
	v_add_f32_e32 v20, v210, v26
	v_add_f32_e32 v20, v211, v20
	v_add_f32_e32 v20, v212, v20
	v_add_f32_e32 v30, v213, v20
	v_sub_f32_e32 v20, v21, v66
	v_exp_f32_e32 v214, v20
	v_lshl_add_u64 v[20:21], v[142:143], 0, v[176:177]
	v_lshl_add_u64 v[20:21], v[20:21], 0, s[0:1]
	global_load_lds_dwordx4 v[20:21], off
	v_lshlrev_b32_e32 v20, 1, v157
	v_mov_b32_e32 v21, v177
	v_lshl_add_u64 v[20:21], v[144:145], 0, v[20:21]
	v_lshl_add_u64 v[20:21], v[20:21], 0, s[0:1]
	s_mov_b32 m0, s8
	v_lshlrev_b32_e32 v142, 9, v154
	global_load_lds_dwordx4 v[20:21], off
	v_lshl_add_u64 v[20:21], v[146:147], 0, v[176:177]
	v_lshl_add_u64 v[20:21], v[20:21], 0, s[0:1]
	s_mov_b32 m0, s9
	v_lshlrev_b32_e32 v176, 1, v158
	global_load_lds_dwordx4 v[20:21], off
	v_lshl_add_u64 v[20:21], v[148:149], 0, v[176:177]
	v_lshl_add_u64 v[20:21], v[20:21], 0, s[0:1]
	s_mov_b32 m0, s7
	v_cvt_pk_bf16_f32 v42, v67, v68
	global_load_lds_dwordx4 v[20:21], off
	v_lshrrev_b32_e32 v20, 3, v153
	v_add_u32_e32 v31, v20, v152
	v_xor_b32_e32 v20, v31, v151
	v_lshlrev_b32_e32 v46, 4, v20
	v_add3_u32 v47, 0, v46, v142
	ds_read_b128 v[26:29], v47
	v_add_u32_e32 v21, 8, v31
	v_xor_b32_e32 v21, v21, v151
	v_lshlrev_b32_e32 v67, 4, v21
	ds_read_b128 v[34:37], v47 offset:2048
	ds_read_b128 v[38:41], v47 offset:16384
	v_cvt_pk_bf16_f32 v44, v74, v108
	ds_read_b128 v[52:55], v47 offset:18432
	v_add3_u32 v74, 0, v67, v142
	ds_read_b128 v[56:59], v74
	v_cvt_pk_bf16_f32 v43, v69, v71
	v_cvt_pk_bf16_f32 v45, v110, v132
	v_sub_f32_e32 v20, v22, v66
	v_exp_f32_e32 v108, v20
	s_waitcnt lgkmcnt(0)
	v_mfma_f32_16x16x32_bf16 v[26:29], v[26:29], v[42:45], 0
	ds_read_b128 v[60:63], v74 offset:2048
	ds_read_b128 v[90:93], v74 offset:16384
	v_sub_f32_e32 v68, v23, v66
	ds_read_b128 v[20:23], v74 offset:18432
	v_bitop3_b32 v31, v31, v151, 16 bitop3:0x36
	v_lshlrev_b32_e32 v31, 4, v31
	v_mfma_f32_16x16x32_bf16 v[34:37], v[34:37], v[42:45], 0
	v_sub_f32_e32 v16, v16, v66
	v_add_f32_e32 v30, v214, v30
	v_add_f32_e32 v30, v108, v30
	v_mfma_f32_16x16x32_bf16 v[38:41], v[38:41], v[42:45], 0
	v_sub_f32_e32 v12, v12, v66
	v_sub_f32_e32 v8, v8, v66
	v_sub_f32_e32 v5, v5, v66
	v_mfma_f32_16x16x32_bf16 v[42:45], v[52:55], v[42:45], 0
	v_cvt_pk_bf16_f32 v52, v70, v77
	v_cvt_pk_bf16_f32 v53, v78, v109
	v_cvt_pk_bf16_f32 v54, v111, v122
	v_cvt_pk_bf16_f32 v55, v129, v133
	v_add3_u32 v77, 0, v31, v142
	v_exp_f32_e32 v78, v68
	v_mfma_f32_16x16x32_bf16 v[26:29], v[56:59], v[52:55], v[26:29]
	ds_read_b128 v[56:59], v77
	v_sub_f32_e32 v4, v4, v66
	v_add_f32_e32 v30, v78, v30
	s_waitcnt lgkmcnt(0)
	v_mfma_f32_16x16x32_bf16 v[34:37], v[60:63], v[52:55], v[34:37]
	ds_read_b128 v[60:63], v77 offset:2048
	ds_read_b128 v[68:71], v77 offset:16384
	v_sub_f32_e32 v6, v6, v66
	v_sub_f32_e32 v0, v0, v66
	v_mfma_f32_16x16x32_bf16 v[38:41], v[90:93], v[52:55], v[38:41]
	v_sub_f32_e32 v1, v1, v66
	v_lshlrev_b32_e32 v176, 1, v150
	v_mfma_f32_16x16x32_bf16 v[20:23], v[20:23], v[52:55], v[42:45]
	ds_read_b128 v[52:55], v77 offset:18432
	s_waitcnt vmcnt(8)
	s_barrier
	s_nop 0
	v_cvt_pk_bf16_f32 v42, v79, v120
	v_cvt_pk_bf16_f32 v43, v121, v123
	v_cvt_pk_bf16_f32 v44, v128, v130
	v_cvt_pk_bf16_f32 v45, v131, v134
	v_exp_f32_e32 v79, v16
	v_sub_f32_e32 v16, v17, v66
	v_mfma_f32_16x16x32_bf16 v[26:29], v[56:59], v[42:45], v[26:29]
	ds_read_b128 v[56:59], v47 offset:32768
	s_waitcnt lgkmcnt(0)
	v_mfma_f32_16x16x32_bf16 v[34:37], v[60:63], v[42:45], v[34:37]
	v_cvt_pk_bf16_f32 v60, v76, v100
	v_cvt_pk_bf16_f32 v61, v101, v103
	v_cvt_pk_bf16_f32 v62, v112, v114
	v_mfma_f32_16x16x32_bf16 v[38:41], v[68:71], v[42:45], v[38:41]
	v_cvt_pk_bf16_f32 v63, v116, v117
	v_exp_f32_e32 v68, v16
	v_add_f32_e32 v16, v79, v30
	v_mfma_f32_16x16x32_bf16 v[20:23], v[52:55], v[42:45], v[20:23]
	ds_read_b128 v[42:45], v47 offset:34816
	ds_read_b128 v[52:55], v47 offset:49152
	v_add_f32_e32 v30, v68, v16
	v_sub_f32_e32 v16, v18, v66
	v_mfma_f32_16x16x32_bf16 v[26:29], v[56:59], v[60:63], v[26:29]
	ds_read_b128 v[56:59], v47 offset:51200
	v_exp_f32_e32 v69, v16
	v_exp_f32_e32 v71, v12
	s_waitcnt lgkmcnt(0)
	v_mfma_f32_16x16x32_bf16 v[34:37], v[42:45], v[60:63], v[34:37]
	ds_read_b128 v[42:45], v74 offset:32768
	v_sub_f32_e32 v47, v19, v66
	v_exp_f32_e32 v70, v47
	v_mfma_f32_16x16x32_bf16 v[38:41], v[52:55], v[60:63], v[38:41]
	ds_read_b128 v[16:19], v74 offset:34816
	ds_read_b128 v[52:55], v74 offset:49152
	v_sub_f32_e32 v12, v13, v66
	v_sub_f32_e32 v13, v14, v66
	v_mfma_f32_16x16x32_bf16 v[20:23], v[56:59], v[60:63], v[20:23]
	v_cvt_pk_bf16_f32 v56, v102, v113
	v_cvt_pk_bf16_f32 v57, v97, v115
	v_cvt_pk_bf16_f32 v58, v99, v118
	v_cvt_pk_bf16_f32 v59, v119, v125
	v_add_f32_e32 v30, v69, v30
	v_add3_u32 v14, s22, v46, v142
	s_waitcnt lgkmcnt(0)
	v_mfma_f32_16x16x32_bf16 v[26:29], v[42:45], v[56:59], v[26:29]
	ds_read_b128 v[42:45], v74 offset:51200
	v_add_f32_e32 v30, v70, v30
	v_sub_f32_e32 v46, v15, v66
	v_mfma_f32_16x16x32_bf16 v[16:19], v[16:19], v[56:59], v[34:37]
	s_nop 2
	ds_read_b128 v[34:37], v77 offset:32768
	s_waitcnt lgkmcnt(0)
	v_mfma_f32_16x16x32_bf16 v[20:23], v[42:45], v[56:59], v[20:23]
	v_cvt_pk_bf16_f32 v42, v96, v98
	v_cvt_pk_bf16_f32 v43, v104, v105
	v_cvt_pk_bf16_f32 v44, v106, v107
	v_cvt_pk_bf16_f32 v45, v124, v126
	v_mfma_f32_16x16x32_bf16 v[38:41], v[52:55], v[56:59], v[38:41]
	ds_read_b128 v[52:55], v77 offset:34816
	ds_read_b128 v[60:63], v77 offset:49152
	v_exp_f32_e32 v74, v12
	v_add_f32_e32 v12, v71, v30
	v_mfma_f32_16x16x32_bf16 v[26:29], v[34:37], v[42:45], v[26:29]
	ds_read_b128 v[34:37], v77 offset:51200
	s_waitcnt vmcnt(4)
	s_barrier
	s_waitcnt lgkmcnt(0)
	v_mfma_f32_16x16x32_bf16 v[38:41], v[60:63], v[42:45], v[38:41]
	v_exp_f32_e32 v60, v13
	v_add_f32_e32 v12, v74, v12
	v_cvt_pk_bf16_f32 v56, v80, v81
	v_mfma_f32_16x16x32_bf16 v[16:19], v[52:55], v[42:45], v[16:19]
	ds_read_b128 v[52:55], v14
	v_cvt_pk_bf16_f32 v57, v82, v84
	v_cvt_pk_bf16_f32 v58, v85, v87
	v_mfma_f32_16x16x32_bf16 v[20:23], v[34:37], v[42:45], v[20:23]
	ds_read_b128 v[34:37], v14 offset:2048
	ds_read_b128 v[42:45], v14 offset:16384
	v_cvt_pk_bf16_f32 v59, v89, v94
	v_add_f32_e32 v30, v60, v12
	ds_read_b128 v[12:15], v14 offset:18432
	v_exp_f32_e32 v61, v46
	v_add3_u32 v46, s22, v67, v142
	s_waitcnt lgkmcnt(0)
	v_mfma_f32_16x16x32_bf16 v[16:19], v[34:37], v[56:59], v[16:19]
	ds_read_b128 v[34:37], v46
	v_exp_f32_e32 v62, v8
	v_sub_f32_e32 v8, v9, v66
	v_mfma_f32_16x16x32_bf16 v[26:29], v[52:55], v[56:59], v[26:29]
	v_add3_u32 v9, s22, v31, v142
	v_exp_f32_e32 v63, v8
	v_add_f32_e32 v30, v61, v30
	v_mfma_f32_16x16x32_bf16 v[12:15], v[12:15], v[56:59], v[20:23]
	v_add_f32_e32 v8, v62, v30
	v_add_f32_e32 v67, v63, v8
	v_sub_f32_e32 v8, v10, v66
	v_cvt_pk_bf16_f32 v20, v83, v86
	v_cvt_pk_bf16_f32 v21, v73, v88
	v_cvt_pk_bf16_f32 v22, v95, v75
	v_cvt_pk_bf16_f32 v23, v127, v135
	v_mfma_f32_16x16x32_bf16 v[38:41], v[42:45], v[56:59], v[38:41]
	ds_read_b128 v[42:45], v46 offset:2048
	ds_read_b128 v[52:55], v46 offset:16384
	v_sub_f32_e32 v30, v11, v66
	v_xor_b32_e32 v31, v152, v151
	s_waitcnt lgkmcnt(0)
	v_mfma_f32_16x16x32_bf16 v[26:29], v[34:37], v[20:23], v[26:29]
	ds_read_b128 v[34:37], v46 offset:18432
	v_lshlrev_b32_e32 v31, 4, v31
	v_add3_u32 v31, s34, v31, v142
	v_mfma_f32_16x16x32_bf16 v[16:19], v[42:45], v[20:23], v[16:19]
	ds_read_b128 v[42:45], v9
	v_mfma_f32_16x16x32_bf16 v[38:41], v[52:55], v[20:23], v[38:41]
	ds_read_b128 v[52:55], v9 offset:2048
	ds_read_b128 v[56:59], v9 offset:16384
	s_waitcnt lgkmcnt(0)
	v_mfma_f32_16x16x32_bf16 v[12:15], v[34:37], v[20:23], v[12:15]
	v_cvt_pk_bf16_f32 v20, v72, v136
	v_cvt_pk_bf16_f32 v21, v137, v138
	v_cvt_pk_bf16_f32 v22, v139, v159
	v_cvt_pk_bf16_f32 v23, v160, v161
	s_nop 1
	v_mfma_f32_16x16x32_bf16 v[16:19], v[52:55], v[20:23], v[16:19]
	v_exp_f32_e32 v52, v8
	ds_read_b128 v[8:11], v9 offset:18432
	s_waitcnt vmcnt(0)
	v_mfma_f32_16x16x32_bf16 v[34:37], v[56:59], v[20:23], v[38:41]
	s_barrier
	v_exp_f32_e32 v53, v30
	v_xor_b32_e32 v30, v155, v151
	ds_read_b128 v[38:41], v31
	v_mfma_f32_16x16x32_bf16 v[26:29], v[42:45], v[20:23], v[26:29]
	v_cvt_pk_bf16_f32 v42, v48, v49
	v_cvt_pk_bf16_f32 v43, v50, v51
	v_cvt_pk_bf16_f32 v44, v162, v33
	s_waitcnt lgkmcnt(0)
	v_mfma_f32_16x16x32_bf16 v[8:11], v[8:11], v[20:23], v[12:15]
	s_nop 2
	ds_read_b128 v[12:15], v31 offset:2048
	ds_read_b128 v[20:23], v31 offset:16384
	v_cvt_pk_bf16_f32 v45, v163, v164
	v_cvt_pk_bf16_f32 v33, v169, v170
	v_exp_f32_e32 v51, v4
	s_waitcnt lgkmcnt(0)
	v_mfma_f32_16x16x32_bf16 v[12:15], v[12:15], v[42:45], v[16:19]
	v_add_f32_e32 v4, v52, v67
	v_add_f32_e32 v4, v53, v4
	v_add_f32_e32 v4, v51, v4
	v_lshlrev_b32_e32 v16, 4, v30
	v_add3_u32 v50, s34, v16, v142
	v_mfma_f32_16x16x32_bf16 v[26:29], v[38:41], v[42:45], v[26:29]
	ds_read_b128 v[38:41], v31 offset:18432
	ds_read_b128 v[16:19], v50
	v_cvt_pk_bf16_f32 v30, v32, v165
	v_mfma_f32_16x16x32_bf16 v[20:23], v[20:23], v[42:45], v[34:37]
	s_nop 2
	ds_read_b128 v[34:37], v50 offset:2048
	ds_read_b128 v[46:49], v50 offset:16384
	v_cvt_pk_bf16_f32 v31, v166, v167
	v_cvt_pk_bf16_f32 v32, v168, v25
	s_waitcnt lgkmcnt(0)
	v_mfma_f32_16x16x32_bf16 v[8:11], v[38:41], v[42:45], v[8:11]
	v_cvt_pk_bf16_f32 v38, v24, v171
	v_cvt_pk_bf16_f32 v39, v172, v173
	v_cvt_pk_bf16_f32 v40, v174, v175
	v_mfma_f32_16x16x32_bf16 v[16:19], v[16:19], v[30:33], v[26:29]
	v_cvt_pk_bf16_f32 v41, v178, v179
	s_nop 1
	ds_read_b128 v[26:29], v50 offset:18432
	v_exp_f32_e32 v50, v5
	v_bitop3_b32 v5, v152, v151, 8 bitop3:0x36
	v_lshlrev_b32_e32 v5, 4, v5
	v_add3_u32 v5, s34, v5, v142
	v_mfma_f32_16x16x32_bf16 v[12:15], v[34:37], v[30:33], v[12:15]
	ds_read_b128 v[34:37], v5
	v_add_f32_e32 v4, v50, v4
	v_mfma_f32_16x16x32_bf16 v[20:23], v[46:49], v[30:33], v[20:23]
	v_exp_f32_e32 v47, v6
	s_waitcnt lgkmcnt(0)
	v_mfma_f32_16x16x32_bf16 v[8:11], v[26:29], v[30:33], v[8:11]
	ds_read_b128 v[26:29], v5 offset:2048
	ds_read_b128 v[30:33], v5 offset:16384
	v_mfma_f32_16x16x32_bf16 v[16:19], v[34:37], v[38:41], v[16:19]
	ds_read_b128 v[34:37], v5 offset:18432
	v_bitop3_b32 v5, v152, v151, 12 bitop3:0x36
	v_lshlrev_b32_e32 v5, 4, v5
	v_add3_u32 v46, s34, v5, v142
	s_waitcnt lgkmcnt(0)
	v_mfma_f32_16x16x32_bf16 v[12:15], v[26:29], v[38:41], v[12:15]
	ds_read_b128 v[24:27], v46
	v_sub_f32_e32 v5, v7, v66
	v_mfma_f32_16x16x32_bf16 v[20:23], v[30:33], v[38:41], v[20:23]
	ds_read_b128 v[28:31], v46 offset:2048
	ds_read_b128 v[42:45], v46 offset:16384
	v_cvt_pk_bf16_f32 v32, v180, v181
	v_cvt_pk_bf16_f32 v33, v182, v183
	v_mfma_f32_16x16x32_bf16 v[8:11], v[34:37], v[38:41], v[8:11]
	v_exp_f32_e32 v40, v5
	v_cvt_pk_bf16_f32 v34, v184, v185
	v_cvt_pk_bf16_f32 v35, v186, v187
	v_exp_f32_e32 v41, v0
	s_waitcnt lgkmcnt(0)
	v_mfma_f32_16x16x32_bf16 v[16:19], v[24:27], v[32:35], v[16:19]
	v_add_f32_e32 v24, v47, v4
	v_add_f32_e32 v36, v40, v24
	v_bitop3_b32 v24, v152, v151, 16 bitop3:0x36
	v_lshlrev_b32_e32 v24, 4, v24
	v_mfma_f32_16x16x32_bf16 v[4:7], v[28:31], v[32:35], v[12:15]
	v_add3_u32 v37, s34, v24, v142
	ds_read_b128 v[24:27], v37
	v_add_f32_e32 v0, v41, v36
	ds_read_b128 v[12:15], v46 offset:18432
	v_mfma_f32_16x16x32_bf16 v[20:23], v[42:45], v[32:35], v[20:23]
	v_bitop3_b32 v36, v152, v151, 20 bitop3:0x36
	s_waitcnt lgkmcnt(0)
	v_mfma_f32_16x16x32_bf16 v[8:11], v[12:15], v[32:35], v[8:11]
	ds_read_b128 v[12:15], v37 offset:2048
	ds_read_b128 v[28:31], v37 offset:16384
	v_cvt_pk_bf16_f32 v32, v188, v189
	v_cvt_pk_bf16_f32 v33, v207, v208
	v_cvt_pk_bf16_f32 v34, v209, v210
	v_cvt_pk_bf16_f32 v35, v211, v212
	s_nop 1
	v_mfma_f32_16x16x32_bf16 v[16:19], v[24:27], v[32:35], v[16:19]
	ds_read_b128 v[24:27], v37 offset:18432
	s_waitcnt lgkmcnt(0)
	v_mfma_f32_16x16x32_bf16 v[4:7], v[12:15], v[32:35], v[4:7]
	v_lshlrev_b32_e32 v12, 4, v36
	v_add3_u32 v42, s34, v12, v142
	ds_read_b128 v[12:15], v42
	v_mfma_f32_16x16x32_bf16 v[20:23], v[28:31], v[32:35], v[20:23]
	ds_read_b128 v[28:31], v42 offset:2048
	ds_read_b128 v[36:39], v42 offset:16384
	v_mfma_f32_16x16x32_bf16 v[8:11], v[24:27], v[32:35], v[8:11]
	v_exp_f32_e32 v32, v1
	v_sub_f32_e32 v1, v2, v66
	v_exp_f32_e32 v33, v1
	v_cvt_pk_bf16_f32 v24, v213, v214
	v_cvt_pk_bf16_f32 v25, v108, v78
	v_cvt_pk_bf16_f32 v26, v79, v68
	v_cvt_pk_bf16_f32 v27, v69, v70
	v_add_f32_e32 v0, v32, v0
	v_add_f32_e32 v34, v33, v0
	s_waitcnt lgkmcnt(0)
	v_mfma_f32_16x16x32_bf16 v[12:15], v[12:15], v[24:27], v[16:19]
	v_bitop3_b32 v0, v152, v151, 24 bitop3:0x36
	v_lshlrev_b32_e32 v0, 4, v0
	v_add3_u32 v35, s34, v0, v142
	ds_read_b128 v[16:19], v42 offset:18432
	v_mfma_f32_16x16x32_bf16 v[4:7], v[28:31], v[24:27], v[4:7]
	ds_read_b128 v[28:31], v35
	v_mfma_f32_16x16x32_bf16 v[20:23], v[36:39], v[24:27], v[20:23]
	v_sub_f32_e32 v36, v3, v66
	v_exp_f32_e32 v36, v36
	s_waitcnt lgkmcnt(0)
	v_mfma_f32_16x16x32_bf16 v[0:3], v[16:19], v[24:27], v[8:11]
	s_nop 2
	ds_read_b128 v[8:11], v35 offset:2048
	ds_read_b128 v[16:19], v35 offset:16384
	v_cvt_pk_bf16_f32 v24, v71, v74
	v_cvt_pk_bf16_f32 v25, v60, v61
	v_cvt_pk_bf16_f32 v26, v62, v63
	v_cvt_pk_bf16_f32 v27, v52, v53
	v_add_f32_e32 v34, v36, v34
	ds_bpermute_b32 v37, v65, v34
	v_mfma_f32_16x16x32_bf16 v[12:15], v[28:31], v[24:27], v[12:15]
	ds_read_b128 v[28:31], v35 offset:18432
	v_bitop3_b32 v35, v152, v151, 28 bitop3:0x36
	s_waitcnt lgkmcnt(0)
	v_mfma_f32_16x16x32_bf16 v[4:7], v[8:11], v[24:27], v[4:7]
	v_lshlrev_b32_e32 v8, 4, v35
	v_add3_u32 v35, s34, v8, v142
	ds_read_b128 v[8:11], v35
	v_mfma_f32_16x16x32_bf16 v[16:19], v[16:19], v[24:27], v[20:23]
	s_nop 2
	ds_read_b128 v[20:23], v35 offset:2048
	v_mfma_f32_16x16x32_bf16 v[0:3], v[28:31], v[24:27], v[0:3]
	v_cvt_pk_bf16_f32 v24, v51, v50
	v_cvt_pk_bf16_f32 v25, v47, v40
	v_cvt_pk_bf16_f32 v26, v41, v32
	v_cvt_pk_bf16_f32 v27, v33, v36
	v_add_f32_e32 v28, v34, v37
	ds_bpermute_b32 v29, v64, v28
	s_waitcnt lgkmcnt(0)
	v_mfma_f32_16x16x32_bf16 v[8:11], v[8:11], v[24:27], v[12:15]
	s_nop 2
	ds_read_b128 v[12:15], v35 offset:16384
	v_mfma_f32_16x16x32_bf16 v[4:7], v[20:23], v[24:27], v[4:7]
	ds_read_b128 v[20:23], v35 offset:18432
	s_waitcnt lgkmcnt(0)
	v_mfma_f32_16x16x32_bf16 v[12:15], v[12:15], v[24:27], v[16:19]
	s_nop 2
	v_add_f32_e32 v16, v28, v29
	v_div_scale_f32 v17, s[0:1], v16, v16, 1.0
	v_rcp_f32_e32 v18, v17
	v_readlane_b32 s0, v253, 0
	v_readlane_b32 s1, v253, 1
	v_mfma_f32_16x16x32_bf16 v[0:3], v[20:23], v[24:27], v[0:3]
	v_fma_f32 v19, -v17, v18, 1.0
	v_fmac_f32_e32 v18, v19, v18
	v_div_scale_f32 v19, vcc, 1.0, v16, 1.0
	v_mul_f32_e32 v20, v19, v18
	s_load_dwordx16 s[4:19], s[0:1], 0xf0
	v_fma_f32 v21, -v17, v20, v19
	v_fmac_f32_e32 v20, v21, v18
	v_fma_f32 v17, -v17, v20, v19
	v_div_fmas_f32 v17, v17, v18, v20
	v_lshlrev_b64 v[18:19], 12, v[140:141]
	v_div_fixup_f32 v16, v17, v16, 1.0
	s_waitcnt lgkmcnt(0)
	v_lshl_add_u64 v[18:19], s[18:19], 0, v[18:19]
	v_lshl_add_u64 v[18:19], v[18:19], 0, s[70:71]
	v_pk_mul_f32 v[10:11], v[10:11], v[16:17] op_sel_hi:[1,0]
	v_pk_mul_f32 v[8:9], v[8:9], v[16:17] op_sel_hi:[1,0]
	v_pk_mul_f32 v[20:21], v[6:7], v[16:17] op_sel_hi:[1,0]
	v_pk_mul_f32 v[6:7], v[4:5], v[16:17] op_sel_hi:[1,0]
	v_lshl_add_u64 v[18:19], v[18:19], 0, v[176:177]
	v_cvt_pk_bf16_f32 v4, v8, v9
	v_cvt_pk_bf16_f32 v5, v10, v11
	v_cvt_pk_bf16_f32 v6, v6, v7
	v_cvt_pk_bf16_f32 v7, v20, v21
	global_store_dwordx4 v[18:19], v[4:7], off offset:2048
	v_pk_mul_f32 v[8:9], v[2:3], v[16:17] op_sel_hi:[1,0]
	v_pk_mul_f32 v[2:3], v[0:1], v[16:17] op_sel_hi:[1,0]
	v_pk_mul_f32 v[4:5], v[14:15], v[16:17] op_sel_hi:[1,0]
	v_pk_mul_f32 v[6:7], v[12:13], v[16:17] op_sel_hi:[1,0]
	v_cvt_pk_bf16_f32 v1, v4, v5
	v_cvt_pk_bf16_f32 v0, v6, v7
	v_cvt_pk_bf16_f32 v2, v2, v3
	v_cvt_pk_bf16_f32 v3, v8, v9
	global_store_dwordx4 v[18:19], v[0:3], off offset:2112
	s_cbranch_scc1 .LBB0_383

.LBB0_767:
	s_cmpk_gt_i32 s30, 0x7ff
	s_waitcnt vmcnt(0)
	s_barrier
	s_cbranch_scc1 .LBB0_922
	v_readlane_b32 s0, v252, 19
	s_lshl_b32 s0, s0, 3
	v_readlane_b32 s1, v252, 20
	v_writelane_b32 v252, s0, 32
	s_nop 0
	v_readlane_b32 s35, v252, 28
	s_movk_i32 s100, 0x7ff
	s_mov_b32 s101, 0
	v_readlane_b32 s0, v253, 6
	s_cmp_lt_u32 s0, 12
	s_cbranch_scc0 .Lc2b_go_b
	s_cmpk_eq_i32 s94, 0x100
	s_cbranch_scc0 .Lc2b_go_b
	s_cmpk_lt_i32 s35, 0x80
	s_cbranch_scc0 .Lc2b_hi_b
	s_movk_i32 s100, 0x4ff
	s_branch .Lc2b_go_b

.LBB0_769:
	s_or_b64 exec, exec, s[0:1]
	s_mov_b32 s0, 0xff800000
	v_max3_f32 v64, v109, s0, v108
	v_max3_f32 v64, v64, v111, v110
	v_max3_f32 v64, v64, v133, v132
	v_max3_f32 v64, v64, v135, v134
	v_max3_f32 v64, v64, v137, v136
	v_max3_f32 v64, v64, v121, v120
	v_max3_f32 v64, v64, v123, v122
	v_max3_f32 v64, v64, v129, v128
	v_max3_f32 v64, v64, v131, v130
	v_max3_f32 v64, v64, v101, v100
	v_max3_f32 v64, v64, v103, v102
	v_max3_f32 v64, v64, v113, v112
	v_max3_f32 v64, v64, v115, v114
	v_max3_f32 v64, v64, v117, v116
	v_max3_f32 v64, v64, v119, v118
	v_max3_f32 v64, v64, v125, v124
	v_max3_f32 v64, v64, v127, v126
	v_max3_f32 v64, v64, v97, v96
	v_max3_f32 v64, v64, v99, v98
	v_max3_f32 v64, v64, v105, v104
	v_max3_f32 v64, v64, v107, v106
	v_max3_f32 v64, v64, v81, v80
	v_max3_f32 v64, v64, v83, v82
	v_max3_f32 v64, v64, v93, v92
	v_max3_f32 v64, v64, v95, v94
	v_max3_f32 v64, v64, v85, v84
	v_max3_f32 v64, v64, v87, v86
	v_max3_f32 v64, v64, v89, v88
	v_max3_f32 v64, v64, v91, v90
	v_max3_f32 v64, v64, v73, v72
	v_max3_f32 v64, v64, v139, v75
	v_max3_f32 v64, v64, v167, v166
	v_max3_f32 v64, v64, v169, v168
	v_max3_f32 v64, v64, v160, v159
	v_max3_f32 v64, v64, v162, v161
	v_max3_f32 v64, v64, v164, v163
	v_max3_f32 v64, v64, v48, v49
	v_max3_f32 v64, v64, v50, v51
	v_max3_f32 v64, v64, v32, v33
	v_max3_f32 v64, v64, v34, v35
	v_max3_f32 v64, v64, v36, v37
	v_max3_f32 v64, v64, v38, v39
	v_max3_f32 v64, v64, v24, v25
	v_max3_f32 v64, v64, v26, v27
	v_max3_f32 v64, v64, v56, v57
	v_max3_f32 v64, v64, v58, v59
	v_max3_f32 v64, v64, v40, v41
	v_max3_f32 v64, v64, v42, v43
	v_max3_f32 v64, v64, v44, v45
	v_max3_f32 v64, v64, v46, v47
	v_max3_f32 v64, v64, v28, v29
	v_max3_f32 v64, v64, v30, v31
	v_max3_f32 v64, v64, v60, v61
	v_max3_f32 v64, v64, v62, v63
	v_max3_f32 v64, v64, v52, v53
	v_max3_f32 v64, v64, v54, v55
	v_max3_f32 v64, v64, v20, v21
	v_max3_f32 v64, v64, v22, v23
	v_max3_f32 v64, v64, v16, v17
	v_max3_f32 v64, v64, v18, v19
	v_max3_f32 v64, v64, v12, v13
	v_max3_f32 v64, v64, v14, v15
	v_max3_f32 v64, v64, v8, v9
	v_max3_f32 v64, v64, v10, v11
	v_and_b32_e32 v66, 64, v199
	v_max3_f32 v64, v64, v4, v5
	v_xor_b32_e32 v65, 16, v199
	v_add_u32_e32 v66, 64, v66
	v_max3_f32 v64, v64, v6, v7
	v_cmp_lt_i32_e32 vcc, v65, v66
	v_max3_f32 v64, v64, v0, v1
	v_max3_f32 v64, v64, v2, v3
	v_cndmask_b32_e32 v65, v199, v65, vcc
	v_lshlrev_b32_e32 v65, 2, v65
	ds_bpermute_b32 v67, v65, v64
	v_lshlrev_b32_e32 v176, 1, v156
	s_mov_b64 s[0:1], 0x1000
	s_mov_b32 m0, s10
	s_waitcnt vmcnt(8)
	s_waitcnt lgkmcnt(0)
	v_max_f32_e32 v67, v67, v67
	v_max_f32_e32 v67, v64, v67
	v_xor_b32_e32 v64, 32, v199
	v_cmp_lt_i32_e32 vcc, v64, v66
	s_barrier
	s_add_i32 s35, s35, s94
	v_cndmask_b32_e32 v64, v199, v64, vcc
	v_lshlrev_b32_e32 v64, 2, v64
	ds_bpermute_b32 v66, v64, v67
	s_waitcnt lgkmcnt(0)
	v_max_f32_e32 v66, v66, v66
	v_max_f32_e32 v66, v67, v66
	v_sub_f32_e32 v67, v109, v66
	v_exp_f32_e32 v67, v67
	v_sub_f32_e32 v68, v108, v66
	v_exp_f32_e32 v68, v68
	v_sub_f32_e32 v69, v111, v66
	v_exp_f32_e32 v69, v69
	v_sub_f32_e32 v71, v110, v66
	v_exp_f32_e32 v71, v71
	v_sub_f32_e32 v74, v133, v66
	v_add_f32_e32 v70, 0, v67
	v_exp_f32_e32 v74, v74
	v_add_f32_e32 v70, v68, v70
	v_add_f32_e32 v70, v69, v70
	v_add_f32_e32 v70, v71, v70
	v_add_f32_e32 v76, v74, v70
	v_sub_f32_e32 v70, v132, v66
	v_exp_f32_e32 v108, v70
	v_sub_f32_e32 v70, v135, v66
	v_exp_f32_e32 v110, v70
	v_sub_f32_e32 v70, v134, v66
	v_exp_f32_e32 v132, v70
	v_sub_f32_e32 v70, v137, v66
	v_exp_f32_e32 v70, v70
	v_sub_f32_e32 v77, v136, v66
	v_add_f32_e32 v76, v108, v76
	v_exp_f32_e32 v77, v77
	v_sub_f32_e32 v78, v121, v66
	v_add_f32_e32 v76, v110, v76
	v_exp_f32_e32 v78, v78
	v_sub_f32_e32 v79, v120, v66
	v_add_f32_e32 v76, v132, v76
	v_exp_f32_e32 v109, v79
	v_sub_f32_e32 v79, v123, v66
	v_add_f32_e32 v76, v70, v76
	v_exp_f32_e32 v111, v79
	v_sub_f32_e32 v79, v122, v66
	v_add_f32_e32 v76, v77, v76
	v_exp_f32_e32 v122, v79
	v_sub_f32_e32 v79, v129, v66
	v_add_f32_e32 v76, v78, v76
	v_exp_f32_e32 v129, v79
	v_sub_f32_e32 v79, v128, v66
	v_add_f32_e32 v76, v109, v76
	v_exp_f32_e32 v133, v79
	v_sub_f32_e32 v79, v131, v66
	v_add_f32_e32 v76, v111, v76
	v_exp_f32_e32 v79, v79
	v_sub_f32_e32 v120, v130, v66
	v_add_f32_e32 v76, v122, v76
	v_exp_f32_e32 v120, v120
	v_sub_f32_e32 v101, v101, v66
	v_add_f32_e32 v76, v129, v76
	v_exp_f32_e32 v121, v101
	v_sub_f32_e32 v100, v100, v66
	v_add_f32_e32 v76, v133, v76
	v_exp_f32_e32 v123, v100
	v_sub_f32_e32 v100, v103, v66
	v_add_f32_e32 v76, v79, v76
	v_exp_f32_e32 v128, v100
	v_add_f32_e32 v76, v120, v76
	v_add_f32_e32 v76, v121, v76
	v_add_f32_e32 v76, v123, v76
	v_add_f32_e32 v100, v128, v76
	v_sub_f32_e32 v76, v102, v66
	v_exp_f32_e32 v130, v76
	v_sub_f32_e32 v76, v113, v66
	v_exp_f32_e32 v131, v76
	v_sub_f32_e32 v76, v112, v66
	v_exp_f32_e32 v134, v76
	v_sub_f32_e32 v76, v115, v66
	v_exp_f32_e32 v76, v76
	v_add_f32_e32 v100, v130, v100
	v_add_f32_e32 v100, v131, v100
	v_add_f32_e32 v100, v134, v100
	v_add_f32_e32 v102, v76, v100
	v_sub_f32_e32 v100, v114, v66
	v_exp_f32_e32 v100, v100
	v_sub_f32_e32 v101, v117, v66
	v_exp_f32_e32 v101, v101
	v_sub_f32_e32 v103, v116, v66
	v_exp_f32_e32 v103, v103
	v_sub_f32_e32 v112, v119, v66
	v_exp_f32_e32 v112, v112
	v_add_f32_e32 v102, v100, v102
	v_add_f32_e32 v102, v101, v102
	v_add_f32_e32 v102, v103, v102
	v_add_f32_e32 v113, v112, v102
	v_sub_f32_e32 v102, v118, v66
	v_exp_f32_e32 v114, v102
	v_sub_f32_e32 v102, v125, v66
	v_exp_f32_e32 v116, v102
	v_sub_f32_e32 v102, v124, v66
	v_exp_f32_e32 v117, v102
	v_sub_f32_e32 v102, v127, v66
	v_exp_f32_e32 v102, v102
	v_add_f32_e32 v113, v114, v113
	v_add_f32_e32 v113, v116, v113
	v_add_f32_e32 v113, v117, v113
	v_add_f32_e32 v118, v102, v113
	v_sub_f32_e32 v113, v126, v66
	v_exp_f32_e32 v113, v113
	v_sub_f32_e32 v97, v97, v66
	v_exp_f32_e32 v97, v97
	v_sub_f32_e32 v96, v96, v66
	v_exp_f32_e32 v115, v96
	v_sub_f32_e32 v96, v99, v66
	v_exp_f32_e32 v99, v96
	v_add_f32_e32 v96, v113, v118
	v_add_f32_e32 v96, v97, v96
	v_add_f32_e32 v96, v115, v96
	v_add_f32_e32 v124, v99, v96
	v_sub_f32_e32 v96, v98, v66
	v_exp_f32_e32 v118, v96
	v_sub_f32_e32 v96, v105, v66
	v_exp_f32_e32 v119, v96
	v_sub_f32_e32 v96, v104, v66
	v_exp_f32_e32 v125, v96
	v_sub_f32_e32 v96, v107, v66
	v_exp_f32_e32 v96, v96
	v_add_f32_e32 v98, v118, v124
	v_add_f32_e32 v98, v119, v98
	v_add_f32_e32 v98, v125, v98
	v_add_f32_e32 v107, v96, v98
	v_sub_f32_e32 v98, v106, v66
	v_exp_f32_e32 v98, v98
	v_sub_f32_e32 v81, v81, v66
	v_exp_f32_e32 v104, v81
	v_sub_f32_e32 v80, v80, v66
	v_exp_f32_e32 v105, v80
	v_sub_f32_e32 v80, v83, v66
	v_exp_f32_e32 v106, v80
	v_add_f32_e32 v80, v98, v107
	v_add_f32_e32 v80, v104, v80
	v_add_f32_e32 v80, v105, v80
	v_add_f32_e32 v81, v106, v80
	v_sub_f32_e32 v80, v82, v66
	v_exp_f32_e32 v107, v80
	v_sub_f32_e32 v80, v93, v66
	v_exp_f32_e32 v124, v80
	v_sub_f32_e32 v80, v92, v66
	v_exp_f32_e32 v126, v80
	v_sub_f32_e32 v80, v95, v66
	v_exp_f32_e32 v80, v80
	v_add_f32_e32 v81, v107, v81
	v_add_f32_e32 v81, v124, v81
	v_add_f32_e32 v81, v126, v81
	v_add_f32_e32 v83, v80, v81
	v_sub_f32_e32 v81, v94, v66
	v_exp_f32_e32 v81, v81
	v_sub_f32_e32 v82, v85, v66
	v_exp_f32_e32 v82, v82
	v_sub_f32_e32 v84, v84, v66
	v_exp_f32_e32 v84, v84
	v_sub_f32_e32 v85, v87, v66
	v_exp_f32_e32 v85, v85
	v_add_f32_e32 v83, v81, v83
	v_add_f32_e32 v83, v82, v83
	v_add_f32_e32 v83, v84, v83
	v_add_f32_e32 v92, v85, v83
	v_sub_f32_e32 v83, v86, v66
	v_exp_f32_e32 v87, v83
	v_sub_f32_e32 v83, v89, v66
	v_exp_f32_e32 v89, v83
	v_sub_f32_e32 v83, v88, v66
	v_exp_f32_e32 v94, v83
	v_sub_f32_e32 v83, v91, v66
	v_exp_f32_e32 v83, v83
	v_add_f32_e32 v86, v87, v92
	v_add_f32_e32 v86, v89, v86
	v_add_f32_e32 v86, v94, v86
	v_add_f32_e32 v91, v83, v86
	v_sub_f32_e32 v86, v90, v66
	v_exp_f32_e32 v86, v86
	v_sub_f32_e32 v73, v73, v66
	v_exp_f32_e32 v73, v73
	v_sub_f32_e32 v72, v72, v66
	v_exp_f32_e32 v88, v72
	v_sub_f32_e32 v72, v139, v66
	v_exp_f32_e32 v95, v72
	v_add_f32_e32 v72, v86, v91
	v_add_f32_e32 v72, v73, v72
	v_add_f32_e32 v72, v88, v72
	v_add_f32_e32 v90, v95, v72
	v_sub_f32_e32 v72, v75, v66
	v_exp_f32_e32 v75, v72
	v_sub_f32_e32 v72, v167, v66
	v_exp_f32_e32 v127, v72
	v_sub_f32_e32 v72, v166, v66
	v_exp_f32_e32 v135, v72
	v_sub_f32_e32 v72, v169, v66
	v_exp_f32_e32 v72, v72
	v_sub_f32_e32 v91, v168, v66
	v_add_f32_e32 v90, v75, v90
	v_exp_f32_e32 v136, v91
	v_sub_f32_e32 v91, v160, v66
	v_add_f32_e32 v90, v127, v90
	v_exp_f32_e32 v137, v91
	v_sub_f32_e32 v91, v159, v66
	v_add_f32_e32 v90, v135, v90
	v_exp_f32_e32 v138, v91
	v_sub_f32_e32 v91, v162, v66
	v_add_f32_e32 v90, v72, v90
	v_exp_f32_e32 v139, v91
	v_sub_f32_e32 v91, v161, v66
	v_add_f32_e32 v90, v136, v90
	v_exp_f32_e32 v159, v91
	v_sub_f32_e32 v91, v164, v66
	v_add_f32_e32 v90, v137, v90
	v_exp_f32_e32 v160, v91
	v_sub_f32_e32 v91, v163, v66
	v_add_f32_e32 v90, v138, v90
	v_exp_f32_e32 v161, v91
	v_sub_f32_e32 v48, v48, v66
	v_add_f32_e32 v90, v139, v90
	v_exp_f32_e32 v48, v48
	v_sub_f32_e32 v49, v49, v66
	v_add_f32_e32 v90, v159, v90
	v_exp_f32_e32 v49, v49
	v_sub_f32_e32 v50, v50, v66
	v_add_f32_e32 v90, v160, v90
	v_exp_f32_e32 v50, v50
	v_sub_f32_e32 v51, v51, v66
	v_add_f32_e32 v90, v161, v90
	v_exp_f32_e32 v51, v51
	v_sub_f32_e32 v32, v32, v66
	v_add_f32_e32 v90, v48, v90
	v_exp_f32_e32 v162, v32
	v_add_f32_e32 v32, v49, v90
	v_add_f32_e32 v32, v50, v32
	v_add_f32_e32 v32, v51, v32
	v_add_f32_e32 v90, v162, v32
	v_sub_f32_e32 v32, v33, v66
	v_exp_f32_e32 v33, v32
	v_sub_f32_e32 v32, v34, v66
	v_exp_f32_e32 v163, v32
	v_sub_f32_e32 v32, v35, v66
	v_exp_f32_e32 v164, v32
	v_sub_f32_e32 v32, v36, v66
	v_exp_f32_e32 v32, v32
	v_sub_f32_e32 v35, v37, v66
	v_add_f32_e32 v34, v33, v90
	v_exp_f32_e32 v165, v35
	v_sub_f32_e32 v35, v38, v66
	v_add_f32_e32 v34, v163, v34
	v_exp_f32_e32 v166, v35
	v_sub_f32_e32 v35, v39, v66
	v_add_f32_e32 v34, v164, v34
	v_exp_f32_e32 v167, v35
	v_sub_f32_e32 v24, v24, v66
	v_add_f32_e32 v34, v32, v34
	v_exp_f32_e32 v168, v24
	v_add_f32_e32 v24, v165, v34
	v_add_f32_e32 v24, v166, v24
	v_add_f32_e32 v24, v167, v24
	v_add_f32_e32 v34, v168, v24
	v_sub_f32_e32 v24, v25, v66
	v_exp_f32_e32 v25, v24
	v_sub_f32_e32 v24, v26, v66
	v_exp_f32_e32 v169, v24
	v_sub_f32_e32 v24, v27, v66
	v_exp_f32_e32 v170, v24
	v_sub_f32_e32 v24, v56, v66
	v_exp_f32_e32 v24, v24
	v_sub_f32_e32 v27, v57, v66
	v_add_f32_e32 v26, v25, v34
	v_exp_f32_e32 v171, v27
	v_sub_f32_e32 v27, v58, v66
	v_add_f32_e32 v26, v169, v26
	v_exp_f32_e32 v172, v27
	v_sub_f32_e32 v27, v59, v66
	v_add_f32_e32 v26, v170, v26
	v_exp_f32_e32 v173, v27
	v_sub_f32_e32 v27, v40, v66
	v_add_f32_e32 v26, v24, v26
	v_exp_f32_e32 v174, v27
	v_sub_f32_e32 v27, v41, v66
	v_add_f32_e32 v26, v171, v26
	v_exp_f32_e32 v175, v27
	v_sub_f32_e32 v27, v42, v66
	v_add_f32_e32 v26, v172, v26
	v_exp_f32_e32 v178, v27
	v_sub_f32_e32 v27, v43, v66
	v_add_f32_e32 v26, v173, v26
	v_exp_f32_e32 v179, v27
	v_sub_f32_e32 v27, v44, v66
	v_add_f32_e32 v26, v174, v26
	v_exp_f32_e32 v180, v27
	v_sub_f32_e32 v27, v45, v66
	v_add_f32_e32 v26, v175, v26
	v_exp_f32_e32 v181, v27
	v_sub_f32_e32 v27, v46, v66
	v_add_f32_e32 v26, v178, v26
	v_exp_f32_e32 v182, v27
	v_sub_f32_e32 v27, v47, v66
	v_add_f32_e32 v26, v179, v26
	v_exp_f32_e32 v183, v27
	v_sub_f32_e32 v27, v28, v66
	v_add_f32_e32 v26, v180, v26
	v_exp_f32_e32 v184, v27
	v_sub_f32_e32 v27, v29, v66
	v_add_f32_e32 v26, v181, v26
	v_exp_f32_e32 v185, v27
	v_sub_f32_e32 v27, v30, v66
	v_add_f32_e32 v26, v182, v26
	v_exp_f32_e32 v186, v27
	v_sub_f32_e32 v27, v31, v66
	v_add_f32_e32 v26, v183, v26
	v_exp_f32_e32 v187, v27
	v_sub_f32_e32 v27, v60, v66
	v_add_f32_e32 v26, v184, v26
	v_exp_f32_e32 v188, v27
	v_sub_f32_e32 v27, v61, v66
	v_add_f32_e32 v26, v185, v26
	v_exp_f32_e32 v189, v27
	v_sub_f32_e32 v27, v62, v66
	v_add_f32_e32 v26, v186, v26
	v_exp_f32_e32 v207, v27
	v_sub_f32_e32 v27, v63, v66
	v_add_f32_e32 v26, v187, v26
	v_exp_f32_e32 v208, v27
	v_sub_f32_e32 v27, v52, v66
	v_add_f32_e32 v26, v188, v26
	v_exp_f32_e32 v209, v27
	v_sub_f32_e32 v27, v53, v66
	v_add_f32_e32 v26, v189, v26
	v_exp_f32_e32 v210, v27
	v_sub_f32_e32 v27, v54, v66
	v_add_f32_e32 v26, v207, v26
	v_exp_f32_e32 v211, v27
	v_sub_f32_e32 v27, v55, v66
	v_add_f32_e32 v26, v208, v26
	v_exp_f32_e32 v212, v27
	v_sub_f32_e32 v20, v20, v66
	v_add_f32_e32 v26, v209, v26
	v_exp_f32_e32 v213, v20
	v_add_f32_e32 v20, v210, v26
	v_add_f32_e32 v20, v211, v20
	v_add_f32_e32 v20, v212, v20
	v_add_f32_e32 v30, v213, v20
	v_sub_f32_e32 v20, v21, v66
	v_exp_f32_e32 v214, v20
	v_lshl_add_u64 v[20:21], v[142:143], 0, v[176:177]
	v_lshl_add_u64 v[20:21], v[20:21], 0, s[0:1]
	global_load_lds_dwordx4 v[20:21], off
	v_lshlrev_b32_e32 v20, 1, v157
	v_mov_b32_e32 v21, v177
	v_lshl_add_u64 v[20:21], v[144:145], 0, v[20:21]
	v_lshl_add_u64 v[20:21], v[20:21], 0, s[0:1]
	s_mov_b32 m0, s8
	v_lshlrev_b32_e32 v142, 9, v154
	global_load_lds_dwordx4 v[20:21], off
	v_lshl_add_u64 v[20:21], v[146:147], 0, v[176:177]
	v_lshl_add_u64 v[20:21], v[20:21], 0, s[0:1]
	s_mov_b32 m0, s9
	v_lshlrev_b32_e32 v176, 1, v158
	global_load_lds_dwordx4 v[20:21], off
	v_lshl_add_u64 v[20:21], v[148:149], 0, v[176:177]
	v_lshl_add_u64 v[20:21], v[20:21], 0, s[0:1]
	s_mov_b32 m0, s6
	v_cvt_pk_bf16_f32 v42, v67, v68
	global_load_lds_dwordx4 v[20:21], off
	v_lshrrev_b32_e32 v20, 3, v153
	v_add_u32_e32 v31, v20, v152
	v_xor_b32_e32 v20, v31, v151
	v_lshlrev_b32_e32 v46, 4, v20
	v_add3_u32 v47, 0, v46, v142
	ds_read_b128 v[26:29], v47
	v_add_u32_e32 v21, 8, v31
	v_xor_b32_e32 v21, v21, v151
	v_lshlrev_b32_e32 v67, 4, v21
	ds_read_b128 v[34:37], v47 offset:2048
	ds_read_b128 v[38:41], v47 offset:16384
	v_cvt_pk_bf16_f32 v44, v74, v108
	ds_read_b128 v[52:55], v47 offset:18432
	v_add3_u32 v74, 0, v67, v142
	ds_read_b128 v[56:59], v74
	v_cvt_pk_bf16_f32 v43, v69, v71
	v_cvt_pk_bf16_f32 v45, v110, v132
	v_sub_f32_e32 v20, v22, v66
	v_exp_f32_e32 v108, v20
	s_waitcnt lgkmcnt(0)
	v_mfma_f32_16x16x32_bf16 v[26:29], v[26:29], v[42:45], 0
	ds_read_b128 v[60:63], v74 offset:2048
	ds_read_b128 v[90:93], v74 offset:16384
	v_sub_f32_e32 v68, v23, v66
	ds_read_b128 v[20:23], v74 offset:18432
	v_bitop3_b32 v31, v31, v151, 16 bitop3:0x36
	v_lshlrev_b32_e32 v31, 4, v31
	v_mfma_f32_16x16x32_bf16 v[34:37], v[34:37], v[42:45], 0
	v_sub_f32_e32 v16, v16, v66
	v_add_f32_e32 v30, v214, v30
	v_add_f32_e32 v30, v108, v30
	v_mfma_f32_16x16x32_bf16 v[38:41], v[38:41], v[42:45], 0
	v_sub_f32_e32 v12, v12, v66
	v_sub_f32_e32 v8, v8, v66
	v_sub_f32_e32 v5, v5, v66
	v_mfma_f32_16x16x32_bf16 v[42:45], v[52:55], v[42:45], 0
	v_cvt_pk_bf16_f32 v52, v70, v77
	v_cvt_pk_bf16_f32 v53, v78, v109
	v_cvt_pk_bf16_f32 v54, v111, v122
	v_cvt_pk_bf16_f32 v55, v129, v133
	v_add3_u32 v77, 0, v31, v142
	v_exp_f32_e32 v78, v68
	v_mfma_f32_16x16x32_bf16 v[26:29], v[56:59], v[52:55], v[26:29]
	ds_read_b128 v[56:59], v77
	v_sub_f32_e32 v4, v4, v66
	v_add_f32_e32 v30, v78, v30
	s_waitcnt lgkmcnt(0)
	v_mfma_f32_16x16x32_bf16 v[34:37], v[60:63], v[52:55], v[34:37]
	ds_read_b128 v[60:63], v77 offset:2048
	ds_read_b128 v[68:71], v77 offset:16384
	v_sub_f32_e32 v6, v6, v66
	v_sub_f32_e32 v0, v0, v66
	v_mfma_f32_16x16x32_bf16 v[38:41], v[90:93], v[52:55], v[38:41]
	v_sub_f32_e32 v1, v1, v66
	v_lshlrev_b32_e32 v176, 1, v150
	v_mfma_f32_16x16x32_bf16 v[20:23], v[20:23], v[52:55], v[42:45]
	ds_read_b128 v[52:55], v77 offset:18432
	s_waitcnt vmcnt(8)
	s_barrier
	s_nop 0
	v_cvt_pk_bf16_f32 v42, v79, v120
	v_cvt_pk_bf16_f32 v43, v121, v123
	v_cvt_pk_bf16_f32 v44, v128, v130
	v_cvt_pk_bf16_f32 v45, v131, v134
	v_exp_f32_e32 v79, v16
	v_sub_f32_e32 v16, v17, v66
	v_mfma_f32_16x16x32_bf16 v[26:29], v[56:59], v[42:45], v[26:29]
	ds_read_b128 v[56:59], v47 offset:32768
	s_waitcnt lgkmcnt(0)
	v_mfma_f32_16x16x32_bf16 v[34:37], v[60:63], v[42:45], v[34:37]
	v_cvt_pk_bf16_f32 v60, v76, v100
	v_cvt_pk_bf16_f32 v61, v101, v103
	v_cvt_pk_bf16_f32 v62, v112, v114
	v_mfma_f32_16x16x32_bf16 v[38:41], v[68:71], v[42:45], v[38:41]
	v_cvt_pk_bf16_f32 v63, v116, v117
	v_exp_f32_e32 v68, v16
	v_add_f32_e32 v16, v79, v30
	v_mfma_f32_16x16x32_bf16 v[20:23], v[52:55], v[42:45], v[20:23]
	ds_read_b128 v[42:45], v47 offset:34816
	ds_read_b128 v[52:55], v47 offset:49152
	v_add_f32_e32 v30, v68, v16
	v_sub_f32_e32 v16, v18, v66
	v_mfma_f32_16x16x32_bf16 v[26:29], v[56:59], v[60:63], v[26:29]
	ds_read_b128 v[56:59], v47 offset:51200
	v_exp_f32_e32 v69, v16
	v_exp_f32_e32 v71, v12
	s_waitcnt lgkmcnt(0)
	v_mfma_f32_16x16x32_bf16 v[34:37], v[42:45], v[60:63], v[34:37]
	ds_read_b128 v[42:45], v74 offset:32768
	v_sub_f32_e32 v47, v19, v66
	v_exp_f32_e32 v70, v47
	v_mfma_f32_16x16x32_bf16 v[38:41], v[52:55], v[60:63], v[38:41]
	ds_read_b128 v[16:19], v74 offset:34816
	ds_read_b128 v[52:55], v74 offset:49152
	v_sub_f32_e32 v12, v13, v66
	v_sub_f32_e32 v13, v14, v66
	v_mfma_f32_16x16x32_bf16 v[20:23], v[56:59], v[60:63], v[20:23]
	v_cvt_pk_bf16_f32 v56, v102, v113
	v_cvt_pk_bf16_f32 v57, v97, v115
	v_cvt_pk_bf16_f32 v58, v99, v118
	v_cvt_pk_bf16_f32 v59, v119, v125
	v_add_f32_e32 v30, v69, v30
	v_add3_u32 v14, s22, v46, v142
	s_waitcnt lgkmcnt(0)
	v_mfma_f32_16x16x32_bf16 v[26:29], v[42:45], v[56:59], v[26:29]
	ds_read_b128 v[42:45], v74 offset:51200
	v_add_f32_e32 v30, v70, v30
	v_sub_f32_e32 v46, v15, v66
	v_mfma_f32_16x16x32_bf16 v[16:19], v[16:19], v[56:59], v[34:37]
	s_nop 2
	ds_read_b128 v[34:37], v77 offset:32768
	s_waitcnt lgkmcnt(0)
	v_mfma_f32_16x16x32_bf16 v[20:23], v[42:45], v[56:59], v[20:23]
	v_cvt_pk_bf16_f32 v42, v96, v98
	v_cvt_pk_bf16_f32 v43, v104, v105
	v_cvt_pk_bf16_f32 v44, v106, v107
	v_cvt_pk_bf16_f32 v45, v124, v126
	v_mfma_f32_16x16x32_bf16 v[38:41], v[52:55], v[56:59], v[38:41]
	ds_read_b128 v[52:55], v77 offset:34816
	ds_read_b128 v[60:63], v77 offset:49152
	v_exp_f32_e32 v74, v12
	v_add_f32_e32 v12, v71, v30
	v_mfma_f32_16x16x32_bf16 v[26:29], v[34:37], v[42:45], v[26:29]
	ds_read_b128 v[34:37], v77 offset:51200
	s_waitcnt vmcnt(4)
	s_barrier
	s_waitcnt lgkmcnt(0)
	v_mfma_f32_16x16x32_bf16 v[38:41], v[60:63], v[42:45], v[38:41]
	v_exp_f32_e32 v60, v13
	v_add_f32_e32 v12, v74, v12
	v_cvt_pk_bf16_f32 v56, v80, v81
	v_mfma_f32_16x16x32_bf16 v[16:19], v[52:55], v[42:45], v[16:19]
	ds_read_b128 v[52:55], v14
	v_cvt_pk_bf16_f32 v57, v82, v84
	v_cvt_pk_bf16_f32 v58, v85, v87
	v_mfma_f32_16x16x32_bf16 v[20:23], v[34:37], v[42:45], v[20:23]
	ds_read_b128 v[34:37], v14 offset:2048
	ds_read_b128 v[42:45], v14 offset:16384
	v_cvt_pk_bf16_f32 v59, v89, v94
	v_add_f32_e32 v30, v60, v12
	ds_read_b128 v[12:15], v14 offset:18432
	v_exp_f32_e32 v61, v46
	v_add3_u32 v46, s22, v67, v142
	s_waitcnt lgkmcnt(0)
	v_mfma_f32_16x16x32_bf16 v[16:19], v[34:37], v[56:59], v[16:19]
	ds_read_b128 v[34:37], v46
	v_exp_f32_e32 v62, v8
	v_sub_f32_e32 v8, v9, v66
	v_mfma_f32_16x16x32_bf16 v[26:29], v[52:55], v[56:59], v[26:29]
	v_add3_u32 v9, s22, v31, v142
	v_exp_f32_e32 v63, v8
	v_add_f32_e32 v30, v61, v30
	v_mfma_f32_16x16x32_bf16 v[12:15], v[12:15], v[56:59], v[20:23]
	v_add_f32_e32 v8, v62, v30
	v_add_f32_e32 v67, v63, v8
	v_sub_f32_e32 v8, v10, v66
	v_cvt_pk_bf16_f32 v20, v83, v86
	v_cvt_pk_bf16_f32 v21, v73, v88
	v_cvt_pk_bf16_f32 v22, v95, v75
	v_cvt_pk_bf16_f32 v23, v127, v135
	v_mfma_f32_16x16x32_bf16 v[38:41], v[42:45], v[56:59], v[38:41]
	ds_read_b128 v[42:45], v46 offset:2048
	ds_read_b128 v[52:55], v46 offset:16384
	v_sub_f32_e32 v30, v11, v66
	v_xor_b32_e32 v31, v152, v151
	s_waitcnt lgkmcnt(0)
	v_mfma_f32_16x16x32_bf16 v[26:29], v[34:37], v[20:23], v[26:29]
	ds_read_b128 v[34:37], v46 offset:18432
	v_lshlrev_b32_e32 v31, 4, v31
	v_add3_u32 v31, s34, v31, v142
	v_mfma_f32_16x16x32_bf16 v[16:19], v[42:45], v[20:23], v[16:19]
	ds_read_b128 v[42:45], v9
	v_mfma_f32_16x16x32_bf16 v[38:41], v[52:55], v[20:23], v[38:41]
	ds_read_b128 v[52:55], v9 offset:2048
	ds_read_b128 v[56:59], v9 offset:16384
	s_waitcnt lgkmcnt(0)
	v_mfma_f32_16x16x32_bf16 v[12:15], v[34:37], v[20:23], v[12:15]
	v_cvt_pk_bf16_f32 v20, v72, v136
	v_cvt_pk_bf16_f32 v21, v137, v138
	v_cvt_pk_bf16_f32 v22, v139, v159
	v_cvt_pk_bf16_f32 v23, v160, v161
	s_nop 1
	v_mfma_f32_16x16x32_bf16 v[16:19], v[52:55], v[20:23], v[16:19]
	v_exp_f32_e32 v52, v8
	ds_read_b128 v[8:11], v9 offset:18432
	s_waitcnt vmcnt(0)
	v_mfma_f32_16x16x32_bf16 v[34:37], v[56:59], v[20:23], v[38:41]
	s_barrier
	v_exp_f32_e32 v53, v30
	v_xor_b32_e32 v30, v155, v151
	ds_read_b128 v[38:41], v31
	v_mfma_f32_16x16x32_bf16 v[26:29], v[42:45], v[20:23], v[26:29]
	v_cvt_pk_bf16_f32 v42, v48, v49
	v_cvt_pk_bf16_f32 v43, v50, v51
	v_cvt_pk_bf16_f32 v44, v162, v33
	s_waitcnt lgkmcnt(0)
	v_mfma_f32_16x16x32_bf16 v[8:11], v[8:11], v[20:23], v[12:15]
	s_nop 2
	ds_read_b128 v[12:15], v31 offset:2048
	ds_read_b128 v[20:23], v31 offset:16384
	v_cvt_pk_bf16_f32 v45, v163, v164
	v_cvt_pk_bf16_f32 v33, v169, v170
	v_exp_f32_e32 v51, v4
	s_waitcnt lgkmcnt(0)
	v_mfma_f32_16x16x32_bf16 v[12:15], v[12:15], v[42:45], v[16:19]
	v_add_f32_e32 v4, v52, v67
	v_add_f32_e32 v4, v53, v4
	v_add_f32_e32 v4, v51, v4
	v_lshlrev_b32_e32 v16, 4, v30
	v_add3_u32 v50, s34, v16, v142
	v_mfma_f32_16x16x32_bf16 v[26:29], v[38:41], v[42:45], v[26:29]
	ds_read_b128 v[38:41], v31 offset:18432
	ds_read_b128 v[16:19], v50
	v_cvt_pk_bf16_f32 v30, v32, v165
	v_mfma_f32_16x16x32_bf16 v[20:23], v[20:23], v[42:45], v[34:37]
	s_nop 2
	ds_read_b128 v[34:37], v50 offset:2048
	ds_read_b128 v[46:49], v50 offset:16384
	v_cvt_pk_bf16_f32 v31, v166, v167
	v_cvt_pk_bf16_f32 v32, v168, v25
	s_waitcnt lgkmcnt(0)
	v_mfma_f32_16x16x32_bf16 v[8:11], v[38:41], v[42:45], v[8:11]
	v_cvt_pk_bf16_f32 v38, v24, v171
	v_cvt_pk_bf16_f32 v39, v172, v173
	v_cvt_pk_bf16_f32 v40, v174, v175
	v_mfma_f32_16x16x32_bf16 v[16:19], v[16:19], v[30:33], v[26:29]
	v_cvt_pk_bf16_f32 v41, v178, v179
	s_nop 1
	ds_read_b128 v[26:29], v50 offset:18432
	v_exp_f32_e32 v50, v5
	v_bitop3_b32 v5, v152, v151, 8 bitop3:0x36
	v_lshlrev_b32_e32 v5, 4, v5
	v_add3_u32 v5, s34, v5, v142
	v_mfma_f32_16x16x32_bf16 v[12:15], v[34:37], v[30:33], v[12:15]
	ds_read_b128 v[34:37], v5
	v_add_f32_e32 v4, v50, v4
	v_mfma_f32_16x16x32_bf16 v[20:23], v[46:49], v[30:33], v[20:23]
	v_exp_f32_e32 v47, v6
	s_waitcnt lgkmcnt(0)
	v_mfma_f32_16x16x32_bf16 v[8:11], v[26:29], v[30:33], v[8:11]
	ds_read_b128 v[26:29], v5 offset:2048
	ds_read_b128 v[30:33], v5 offset:16384
	v_mfma_f32_16x16x32_bf16 v[16:19], v[34:37], v[38:41], v[16:19]
	ds_read_b128 v[34:37], v5 offset:18432
	v_bitop3_b32 v5, v152, v151, 12 bitop3:0x36
	v_lshlrev_b32_e32 v5, 4, v5
	v_add3_u32 v46, s34, v5, v142
	s_waitcnt lgkmcnt(0)
	v_mfma_f32_16x16x32_bf16 v[12:15], v[26:29], v[38:41], v[12:15]
	ds_read_b128 v[24:27], v46
	v_sub_f32_e32 v5, v7, v66
	v_mfma_f32_16x16x32_bf16 v[20:23], v[30:33], v[38:41], v[20:23]
	ds_read_b128 v[28:31], v46 offset:2048
	ds_read_b128 v[42:45], v46 offset:16384
	v_cvt_pk_bf16_f32 v32, v180, v181
	v_cvt_pk_bf16_f32 v33, v182, v183
	v_mfma_f32_16x16x32_bf16 v[8:11], v[34:37], v[38:41], v[8:11]
	v_exp_f32_e32 v40, v5
	v_cvt_pk_bf16_f32 v34, v184, v185
	v_cvt_pk_bf16_f32 v35, v186, v187
	v_exp_f32_e32 v41, v0
	s_waitcnt lgkmcnt(0)
	v_mfma_f32_16x16x32_bf16 v[16:19], v[24:27], v[32:35], v[16:19]
	v_add_f32_e32 v24, v47, v4
	v_add_f32_e32 v36, v40, v24
	v_bitop3_b32 v24, v152, v151, 16 bitop3:0x36
	v_lshlrev_b32_e32 v24, 4, v24
	v_mfma_f32_16x16x32_bf16 v[4:7], v[28:31], v[32:35], v[12:15]
	v_add3_u32 v37, s34, v24, v142
	ds_read_b128 v[24:27], v37
	v_add_f32_e32 v0, v41, v36
	ds_read_b128 v[12:15], v46 offset:18432
	v_mfma_f32_16x16x32_bf16 v[20:23], v[42:45], v[32:35], v[20:23]
	v_bitop3_b32 v36, v152, v151, 20 bitop3:0x36
	s_waitcnt lgkmcnt(0)
	v_mfma_f32_16x16x32_bf16 v[8:11], v[12:15], v[32:35], v[8:11]
	ds_read_b128 v[12:15], v37 offset:2048
	ds_read_b128 v[28:31], v37 offset:16384
	v_cvt_pk_bf16_f32 v32, v188, v189
	v_cvt_pk_bf16_f32 v33, v207, v208
	v_cvt_pk_bf16_f32 v34, v209, v210
	v_cvt_pk_bf16_f32 v35, v211, v212
	s_nop 1
	v_mfma_f32_16x16x32_bf16 v[16:19], v[24:27], v[32:35], v[16:19]
	ds_read_b128 v[24:27], v37 offset:18432
	s_waitcnt lgkmcnt(0)
	v_mfma_f32_16x16x32_bf16 v[4:7], v[12:15], v[32:35], v[4:7]
	v_lshlrev_b32_e32 v12, 4, v36
	v_add3_u32 v42, s34, v12, v142
	ds_read_b128 v[12:15], v42
	v_mfma_f32_16x16x32_bf16 v[20:23], v[28:31], v[32:35], v[20:23]
	ds_read_b128 v[28:31], v42 offset:2048
	ds_read_b128 v[36:39], v42 offset:16384
	v_mfma_f32_16x16x32_bf16 v[8:11], v[24:27], v[32:35], v[8:11]
	v_exp_f32_e32 v32, v1
	v_sub_f32_e32 v1, v2, v66
	v_exp_f32_e32 v33, v1
	v_cvt_pk_bf16_f32 v24, v213, v214
	v_cvt_pk_bf16_f32 v25, v108, v78
	v_cvt_pk_bf16_f32 v26, v79, v68
	v_cvt_pk_bf16_f32 v27, v69, v70
	v_add_f32_e32 v0, v32, v0
	v_add_f32_e32 v34, v33, v0
	s_waitcnt lgkmcnt(0)
	v_mfma_f32_16x16x32_bf16 v[12:15], v[12:15], v[24:27], v[16:19]
	v_bitop3_b32 v0, v152, v151, 24 bitop3:0x36
	v_lshlrev_b32_e32 v0, 4, v0
	v_add3_u32 v35, s34, v0, v142
	ds_read_b128 v[16:19], v42 offset:18432
	v_mfma_f32_16x16x32_bf16 v[4:7], v[28:31], v[24:27], v[4:7]
	ds_read_b128 v[28:31], v35
	v_mfma_f32_16x16x32_bf16 v[20:23], v[36:39], v[24:27], v[20:23]
	v_sub_f32_e32 v36, v3, v66
	v_exp_f32_e32 v36, v36
	s_waitcnt lgkmcnt(0)
	v_mfma_f32_16x16x32_bf16 v[0:3], v[16:19], v[24:27], v[8:11]
	s_nop 2
	ds_read_b128 v[8:11], v35 offset:2048
	ds_read_b128 v[16:19], v35 offset:16384
	v_cvt_pk_bf16_f32 v24, v71, v74
	v_cvt_pk_bf16_f32 v25, v60, v61
	v_cvt_pk_bf16_f32 v26, v62, v63
	v_cvt_pk_bf16_f32 v27, v52, v53
	v_add_f32_e32 v34, v36, v34
	ds_bpermute_b32 v37, v65, v34
	v_mfma_f32_16x16x32_bf16 v[12:15], v[28:31], v[24:27], v[12:15]
	ds_read_b128 v[28:31], v35 offset:18432
	v_bitop3_b32 v35, v152, v151, 28 bitop3:0x36
	s_waitcnt lgkmcnt(0)
	v_mfma_f32_16x16x32_bf16 v[4:7], v[8:11], v[24:27], v[4:7]
	v_lshlrev_b32_e32 v8, 4, v35
	v_add3_u32 v35, s34, v8, v142
	ds_read_b128 v[8:11], v35
	v_mfma_f32_16x16x32_bf16 v[16:19], v[16:19], v[24:27], v[20:23]
	s_nop 2
	ds_read_b128 v[20:23], v35 offset:2048
	v_mfma_f32_16x16x32_bf16 v[0:3], v[28:31], v[24:27], v[0:3]
	v_cvt_pk_bf16_f32 v24, v51, v50
	v_cvt_pk_bf16_f32 v25, v47, v40
	v_cvt_pk_bf16_f32 v26, v41, v32
	v_cvt_pk_bf16_f32 v27, v33, v36
	v_add_f32_e32 v28, v34, v37
	ds_bpermute_b32 v29, v64, v28
	s_waitcnt lgkmcnt(0)
	v_mfma_f32_16x16x32_bf16 v[8:11], v[8:11], v[24:27], v[12:15]
	s_nop 2
	ds_read_b128 v[12:15], v35 offset:16384
	v_mfma_f32_16x16x32_bf16 v[4:7], v[20:23], v[24:27], v[4:7]
	ds_read_b128 v[20:23], v35 offset:18432
	s_waitcnt lgkmcnt(0)
	v_mfma_f32_16x16x32_bf16 v[12:15], v[12:15], v[24:27], v[16:19]
	s_nop 2
	v_add_f32_e32 v16, v28, v29
	v_div_scale_f32 v17, s[0:1], v16, v16, 1.0
	v_rcp_f32_e32 v18, v17
	v_readlane_b32 s0, v253, 0
	v_readlane_b32 s1, v253, 1
	v_mfma_f32_16x16x32_bf16 v[0:3], v[20:23], v[24:27], v[0:3]
	v_fma_f32 v19, -v17, v18, 1.0
	v_fmac_f32_e32 v18, v19, v18
	v_div_scale_f32 v19, vcc, 1.0, v16, 1.0
	v_mul_f32_e32 v20, v19, v18
	s_load_dwordx16 s[4:19], s[0:1], 0xf0
	v_fma_f32 v21, -v17, v20, v19
	v_fmac_f32_e32 v20, v21, v18
	v_fma_f32 v17, -v17, v20, v19
	v_div_fmas_f32 v17, v17, v18, v20
	v_lshlrev_b64 v[18:19], 12, v[140:141]
	v_readlane_b32 s0, v252, 26
	v_div_fixup_f32 v16, v17, v16, 1.0
	s_waitcnt lgkmcnt(0)
	v_lshl_add_u64 v[18:19], s[18:19], 0, v[18:19]
	s_lshl_b32 s70, s0, 1
	v_lshl_add_u64 v[18:19], v[18:19], 0, s[70:71]
	v_pk_mul_f32 v[10:11], v[10:11], v[16:17] op_sel_hi:[1,0]
	v_pk_mul_f32 v[8:9], v[8:9], v[16:17] op_sel_hi:[1,0]
	v_pk_mul_f32 v[20:21], v[6:7], v[16:17] op_sel_hi:[1,0]
	v_pk_mul_f32 v[6:7], v[4:5], v[16:17] op_sel_hi:[1,0]
	v_lshl_add_u64 v[18:19], v[18:19], 0, v[176:177]
	v_cvt_pk_bf16_f32 v4, v8, v9
	v_cvt_pk_bf16_f32 v5, v10, v11
	v_cvt_pk_bf16_f32 v6, v6, v7
	v_cvt_pk_bf16_f32 v7, v20, v21
	global_store_dwordx4 v[18:19], v[4:7], off offset:2048
	v_pk_mul_f32 v[8:9], v[2:3], v[16:17] op_sel_hi:[1,0]
	v_pk_mul_f32 v[2:3], v[0:1], v[16:17] op_sel_hi:[1,0]
	v_pk_mul_f32 v[4:5], v[14:15], v[16:17] op_sel_hi:[1,0]
	v_pk_mul_f32 v[6:7], v[12:13], v[16:17] op_sel_hi:[1,0]
	v_cvt_pk_bf16_f32 v1, v4, v5
	v_cvt_pk_bf16_f32 v0, v6, v7
	v_cvt_pk_bf16_f32 v2, v2, v3
	v_cvt_pk_bf16_f32 v3, v8, v9
	s_cmp_gt_i32 s35, s100
	s_cbranch_scc0 .Lc2b_c_b
	s_cmp_eq_u32 s101, 0
	s_cbranch_scc1 .Lc2b_c_b
	s_mov_b32 s35, s101
	s_mov_b32 s101, 0
	s_movk_i32 s100, 0x7ff
	s_cmp_gt_i32 s35, s100
.Lc2b_c_b:
	global_store_dwordx4 v[18:19], v[0:3], off offset:2112
	s_cbranch_scc1 .LBB0_922
